# rwkv_ain_phase rewritten by hand: all loads of a thread in one round trip, no LDS staging
# speedup vs baseline: 1.1816x; 1.0036x over previous
.Lain_start:
	s_cmp_lt_u32 s72, 0x80
	s_movk_i32 s11, 0x1000
	s_cselect_b32 s11, 0x100, s11
	s_lshl_b32 s10, s72, 6
	s_add_i32 s2, s11, -1
	s_and_b32 s12, s10, s2
	s_add_i32 s13, s12, 64
	s_add_i32 s4, s10, -1
	s_mul_i32 s4, s4, 0x2180
	s_ashr_i32 s5, s4, 31
	s_add_u32 s4, s4, 0x3382000
	s_addc_u32 s5, s5, 0
	s_add_u32 s4, s4, s76
	s_addc_u32 s5, s5, s77
	v_readlane_b32 s60, v252, 26
	v_readlane_b32 s61, v252, 27
	v_and_b32_e32 v244, 31, v177
	v_lshrrev_b32_e32 v245, 5, v177
	v_cmp_gt_u32_e32 vcc, 24, v244
	s_and_saveexec_b64 s[18:19], vcc
	v_mul_u32_u24_e32 v246, 0x8600, v245
	v_lshl_add_u32 v246, v244, 4, v246
	v_lshlrev_b32_e32 v247, 5, v244
	global_load_dwordx4 v[0:3], v246, s[4:5]
	s_add_u32 s4, s4, 0x2180
	s_addc_u32 s5, s5, 0
	global_load_dwordx4 v[4:7], v246, s[4:5]
	s_add_u32 s4, s4, 0x2180
	s_addc_u32 s5, s5, 0
	global_load_dwordx4 v[8:11], v246, s[4:5]
	s_add_u32 s4, s4, 0x2180
	s_addc_u32 s5, s5, 0
	global_load_dwordx4 v[12:15], v246, s[4:5]
	s_add_u32 s4, s4, 0x2180
	s_addc_u32 s5, s5, 0
	global_load_dwordx4 v[16:19], v246, s[4:5]
	s_add_u32 s4, s4, 0x2180
	s_addc_u32 s5, s5, 0
	global_load_dwordx4 v[20:23], v246, s[4:5]
	s_add_u32 s24, s60, 0x1800
	s_addc_u32 s25, s61, 0
	global_load_dwordx4 v[192:195], v247, s[24:25]
	global_load_dwordx4 v[196:199], v247, s[24:25] offset:16
	s_add_u32 s24, s24, 0x1b00
	s_addc_u32 s25, s25, 0
	global_load_dwordx4 v[200:203], v247, s[24:25]
	global_load_dwordx4 v[204:207], v247, s[24:25] offset:16
	s_add_u32 s24, s24, 0x1b00
	s_addc_u32 s25, s25, 0
	global_load_dwordx4 v[208:211], v247, s[24:25]
	global_load_dwordx4 v[232:235], v247, s[24:25] offset:16
	v_cmp_gt_u32_e64 s[38:39], 8, v244
	v_mov_b32_e32 v248, 0xbfb8aa3b
	v_mov_b32_e32 v251, 0x4038aa3b
	v_cndmask_b32_e64 v248, v248, v251, s[38:39]
	v_cndmask_b32_e64 v249, 1.0, -2.0, s[38:39]
	v_cndmask_b32_e64 v250, 0, 1.0, s[38:39]
	v_add_u32_e32 v251, -8, v244
	v_cmp_gt_u32_e64 s[36:37], 4, v251
	v_cmp_eq_u32_e32 vcc, 0, v245
	s_cmp_eq_u32 s12, 0
	s_cselect_b64 s[30:31], vcc, 0
	v_cmp_eq_u32_e32 vcc, 15, v245
	s_cmp_eq_u32 s13, s11
	s_cselect_b64 s[40:41], vcc, 0
	s_mul_i32 s2, s72, 0x6000
	s_add_u32 s2, s2, 0xf984000
	s_add_u32 s2, s2, s76
	s_addc_u32 s3, s77, 0
	v_mul_u32_u24_e32 v246, 0x600, v245
	v_lshl_add_u32 v246, v244, 4, v246
	s_waitcnt vmcnt(0)
	v_cndmask_b32_e64 v0, v0, 0, s[30:31]
	v_cndmask_b32_e64 v1, v1, 0, s[30:31]
	v_cndmask_b32_e64 v2, v2, 0, s[30:31]
	v_cndmask_b32_e64 v3, v3, 0, s[30:31]
	v_cndmask_b32_e64 v20, v20, 0, s[40:41]
	v_cndmask_b32_e64 v21, v21, 0, s[40:41]
	v_cndmask_b32_e64 v22, v22, 0, s[40:41]
	v_cndmask_b32_e64 v23, v23, 0, s[40:41]
	v_lshlrev_b32_e32 v251, 16, v0
	v_mul_f32_e32 v236, v192, v251
	v_lshlrev_b32_e32 v251, 16, v4
	v_fmac_f32_e32 v236, v200, v251
	v_lshlrev_b32_e32 v251, 16, v8
	v_fmac_f32_e32 v236, v208, v251
	v_and_b32_e32 v251, 0xffff0000, v0
	v_mul_f32_e32 v237, v193, v251
	v_and_b32_e32 v251, 0xffff0000, v4
	v_fmac_f32_e32 v237, v201, v251
	v_and_b32_e32 v251, 0xffff0000, v8
	v_fmac_f32_e32 v237, v209, v251
	v_lshlrev_b32_e32 v251, 16, v1
	v_mul_f32_e32 v238, v194, v251
	v_lshlrev_b32_e32 v251, 16, v5
	v_fmac_f32_e32 v238, v202, v251
	v_lshlrev_b32_e32 v251, 16, v9
	v_fmac_f32_e32 v238, v210, v251
	v_and_b32_e32 v251, 0xffff0000, v1
	v_mul_f32_e32 v239, v195, v251
	v_and_b32_e32 v251, 0xffff0000, v5
	v_fmac_f32_e32 v239, v203, v251
	v_and_b32_e32 v251, 0xffff0000, v9
	v_fmac_f32_e32 v239, v211, v251
	v_lshlrev_b32_e32 v251, 16, v2
	v_mul_f32_e32 v240, v196, v251
	v_lshlrev_b32_e32 v251, 16, v6
	v_fmac_f32_e32 v240, v204, v251
	v_lshlrev_b32_e32 v251, 16, v10
	v_fmac_f32_e32 v240, v232, v251
	v_and_b32_e32 v251, 0xffff0000, v2
	v_mul_f32_e32 v241, v197, v251
	v_and_b32_e32 v251, 0xffff0000, v6
	v_fmac_f32_e32 v241, v205, v251
	v_and_b32_e32 v251, 0xffff0000, v10
	v_fmac_f32_e32 v241, v233, v251
	v_lshlrev_b32_e32 v251, 16, v3
	v_mul_f32_e32 v242, v198, v251
	v_lshlrev_b32_e32 v251, 16, v7
	v_fmac_f32_e32 v242, v206, v251
	v_lshlrev_b32_e32 v251, 16, v11
	v_fmac_f32_e32 v242, v234, v251
	v_and_b32_e32 v251, 0xffff0000, v3
	v_mul_f32_e32 v243, v199, v251
	v_and_b32_e32 v251, 0xffff0000, v7
	v_fmac_f32_e32 v243, v207, v251
	v_and_b32_e32 v251, 0xffff0000, v11
	v_fmac_f32_e32 v243, v235, v251
	v_mul_f32_e32 v251, v248, v236
	v_exp_f32_e32 v251, v251
	s_nop 0
	v_add_f32_e32 v251, 1.0, v251
	v_rcp_f32_e32 v251, v251
	s_nop 0
	v_fma_f32 v251, v251, v249, v250
	v_cndmask_b32_e64 v236, v251, v236, s[36:37]
	v_mul_f32_e32 v251, v248, v237
	v_exp_f32_e32 v251, v251
	s_nop 0
	v_add_f32_e32 v251, 1.0, v251
	v_rcp_f32_e32 v251, v251
	s_nop 0
	v_fma_f32 v251, v251, v249, v250
	v_cndmask_b32_e64 v237, v251, v237, s[36:37]
	v_mul_f32_e32 v251, v248, v238
	v_exp_f32_e32 v251, v251
	s_nop 0
	v_add_f32_e32 v251, 1.0, v251
	v_rcp_f32_e32 v251, v251
	s_nop 0
	v_fma_f32 v251, v251, v249, v250
	v_cndmask_b32_e64 v238, v251, v238, s[36:37]
	v_mul_f32_e32 v251, v248, v239
	v_exp_f32_e32 v251, v251
	s_nop 0
	v_add_f32_e32 v251, 1.0, v251
	v_rcp_f32_e32 v251, v251
	s_nop 0
	v_fma_f32 v251, v251, v249, v250
	v_cndmask_b32_e64 v239, v251, v239, s[36:37]
	v_mul_f32_e32 v251, v248, v240
	v_exp_f32_e32 v251, v251
	s_nop 0
	v_add_f32_e32 v251, 1.0, v251
	v_rcp_f32_e32 v251, v251
	s_nop 0
	v_fma_f32 v251, v251, v249, v250
	v_cndmask_b32_e64 v240, v251, v240, s[36:37]
	v_mul_f32_e32 v251, v248, v241
	v_exp_f32_e32 v251, v251
	s_nop 0
	v_add_f32_e32 v251, 1.0, v251
	v_rcp_f32_e32 v251, v251
	s_nop 0
	v_fma_f32 v251, v251, v249, v250
	v_cndmask_b32_e64 v241, v251, v241, s[36:37]
	v_mul_f32_e32 v251, v248, v242
	v_exp_f32_e32 v251, v251
	s_nop 0
	v_add_f32_e32 v251, 1.0, v251
	v_rcp_f32_e32 v251, v251
	s_nop 0
	v_fma_f32 v251, v251, v249, v250
	v_cndmask_b32_e64 v242, v251, v242, s[36:37]
	v_mul_f32_e32 v251, v248, v243
	v_exp_f32_e32 v251, v251
	s_nop 0
	v_add_f32_e32 v251, 1.0, v251
	v_rcp_f32_e32 v251, v251
	s_nop 0
	v_fma_f32 v251, v251, v249, v250
	v_cndmask_b32_e64 v243, v251, v243, s[36:37]
	v_cvt_pk_bf16_f32 v236, v236, v237
	v_cvt_pk_bf16_f32 v237, v238, v239
	v_cvt_pk_bf16_f32 v238, v240, v241
	v_cvt_pk_bf16_f32 v239, v242, v243
	global_store_dwordx4 v246, v[236:239], s[2:3]
	s_nop 1
	v_lshlrev_b32_e32 v251, 16, v4
	v_mul_f32_e32 v236, v192, v251
	v_lshlrev_b32_e32 v251, 16, v8
	v_fmac_f32_e32 v236, v200, v251
	v_lshlrev_b32_e32 v251, 16, v12
	v_fmac_f32_e32 v236, v208, v251
	v_and_b32_e32 v251, 0xffff0000, v4
	v_mul_f32_e32 v237, v193, v251
	v_and_b32_e32 v251, 0xffff0000, v8
	v_fmac_f32_e32 v237, v201, v251
	v_and_b32_e32 v251, 0xffff0000, v12
	v_fmac_f32_e32 v237, v209, v251
	v_lshlrev_b32_e32 v251, 16, v5
	v_mul_f32_e32 v238, v194, v251
	v_lshlrev_b32_e32 v251, 16, v9
	v_fmac_f32_e32 v238, v202, v251
	v_lshlrev_b32_e32 v251, 16, v13
	v_fmac_f32_e32 v238, v210, v251
	v_and_b32_e32 v251, 0xffff0000, v5
	v_mul_f32_e32 v239, v195, v251
	v_and_b32_e32 v251, 0xffff0000, v9
	v_fmac_f32_e32 v239, v203, v251
	v_and_b32_e32 v251, 0xffff0000, v13
	v_fmac_f32_e32 v239, v211, v251
	v_lshlrev_b32_e32 v251, 16, v6
	v_mul_f32_e32 v240, v196, v251
	v_lshlrev_b32_e32 v251, 16, v10
	v_fmac_f32_e32 v240, v204, v251
	v_lshlrev_b32_e32 v251, 16, v14
	v_fmac_f32_e32 v240, v232, v251
	v_and_b32_e32 v251, 0xffff0000, v6
	v_mul_f32_e32 v241, v197, v251
	v_and_b32_e32 v251, 0xffff0000, v10
	v_fmac_f32_e32 v241, v205, v251
	v_and_b32_e32 v251, 0xffff0000, v14
	v_fmac_f32_e32 v241, v233, v251
	v_lshlrev_b32_e32 v251, 16, v7
	v_mul_f32_e32 v242, v198, v251
	v_lshlrev_b32_e32 v251, 16, v11
	v_fmac_f32_e32 v242, v206, v251
	v_lshlrev_b32_e32 v251, 16, v15
	v_fmac_f32_e32 v242, v234, v251
	v_and_b32_e32 v251, 0xffff0000, v7
	v_mul_f32_e32 v243, v199, v251
	v_and_b32_e32 v251, 0xffff0000, v11
	v_fmac_f32_e32 v243, v207, v251
	v_and_b32_e32 v251, 0xffff0000, v15
	v_fmac_f32_e32 v243, v235, v251
	v_mul_f32_e32 v251, v248, v236
	v_exp_f32_e32 v251, v251
	s_nop 0
	v_add_f32_e32 v251, 1.0, v251
	v_rcp_f32_e32 v251, v251
	s_nop 0
	v_fma_f32 v251, v251, v249, v250
	v_cndmask_b32_e64 v236, v251, v236, s[36:37]
	v_mul_f32_e32 v251, v248, v237
	v_exp_f32_e32 v251, v251
	s_nop 0
	v_add_f32_e32 v251, 1.0, v251
	v_rcp_f32_e32 v251, v251
	s_nop 0
	v_fma_f32 v251, v251, v249, v250
	v_cndmask_b32_e64 v237, v251, v237, s[36:37]
	v_mul_f32_e32 v251, v248, v238
	v_exp_f32_e32 v251, v251
	s_nop 0
	v_add_f32_e32 v251, 1.0, v251
	v_rcp_f32_e32 v251, v251
	s_nop 0
	v_fma_f32 v251, v251, v249, v250
	v_cndmask_b32_e64 v238, v251, v238, s[36:37]
	v_mul_f32_e32 v251, v248, v239
	v_exp_f32_e32 v251, v251
	s_nop 0
	v_add_f32_e32 v251, 1.0, v251
	v_rcp_f32_e32 v251, v251
	s_nop 0
	v_fma_f32 v251, v251, v249, v250
	v_cndmask_b32_e64 v239, v251, v239, s[36:37]
	v_mul_f32_e32 v251, v248, v240
	v_exp_f32_e32 v251, v251
	s_nop 0
	v_add_f32_e32 v251, 1.0, v251
	v_rcp_f32_e32 v251, v251
	s_nop 0
	v_fma_f32 v251, v251, v249, v250
	v_cndmask_b32_e64 v240, v251, v240, s[36:37]
	v_mul_f32_e32 v251, v248, v241
	v_exp_f32_e32 v251, v251
	s_nop 0
	v_add_f32_e32 v251, 1.0, v251
	v_rcp_f32_e32 v251, v251
	s_nop 0
	v_fma_f32 v251, v251, v249, v250
	v_cndmask_b32_e64 v241, v251, v241, s[36:37]
	v_mul_f32_e32 v251, v248, v242
	v_exp_f32_e32 v251, v251
	s_nop 0
	v_add_f32_e32 v251, 1.0, v251
	v_rcp_f32_e32 v251, v251
	s_nop 0
	v_fma_f32 v251, v251, v249, v250
	v_cndmask_b32_e64 v242, v251, v242, s[36:37]
	v_mul_f32_e32 v251, v248, v243
	v_exp_f32_e32 v251, v251
	s_nop 0
	v_add_f32_e32 v251, 1.0, v251
	v_rcp_f32_e32 v251, v251
	s_nop 0
	v_fma_f32 v251, v251, v249, v250
	v_cndmask_b32_e64 v243, v251, v243, s[36:37]
	v_cvt_pk_bf16_f32 v236, v236, v237
	v_cvt_pk_bf16_f32 v237, v238, v239
	v_cvt_pk_bf16_f32 v238, v240, v241
	v_cvt_pk_bf16_f32 v239, v242, v243
	global_store_dwordx4 v246, v[236:239], s[2:3] offset:384
	s_nop 1
	v_lshlrev_b32_e32 v251, 16, v8
	v_mul_f32_e32 v236, v192, v251
	v_lshlrev_b32_e32 v251, 16, v12
	v_fmac_f32_e32 v236, v200, v251
	v_lshlrev_b32_e32 v251, 16, v16
	v_fmac_f32_e32 v236, v208, v251
	v_and_b32_e32 v251, 0xffff0000, v8
	v_mul_f32_e32 v237, v193, v251
	v_and_b32_e32 v251, 0xffff0000, v12
	v_fmac_f32_e32 v237, v201, v251
	v_and_b32_e32 v251, 0xffff0000, v16
	v_fmac_f32_e32 v237, v209, v251
	v_lshlrev_b32_e32 v251, 16, v9
	v_mul_f32_e32 v238, v194, v251
	v_lshlrev_b32_e32 v251, 16, v13
	v_fmac_f32_e32 v238, v202, v251
	v_lshlrev_b32_e32 v251, 16, v17
	v_fmac_f32_e32 v238, v210, v251
	v_and_b32_e32 v251, 0xffff0000, v9
	v_mul_f32_e32 v239, v195, v251
	v_and_b32_e32 v251, 0xffff0000, v13
	v_fmac_f32_e32 v239, v203, v251
	v_and_b32_e32 v251, 0xffff0000, v17
	v_fmac_f32_e32 v239, v211, v251
	v_lshlrev_b32_e32 v251, 16, v10
	v_mul_f32_e32 v240, v196, v251
	v_lshlrev_b32_e32 v251, 16, v14
	v_fmac_f32_e32 v240, v204, v251
	v_lshlrev_b32_e32 v251, 16, v18
	v_fmac_f32_e32 v240, v232, v251
	v_and_b32_e32 v251, 0xffff0000, v10
	v_mul_f32_e32 v241, v197, v251
	v_and_b32_e32 v251, 0xffff0000, v14
	v_fmac_f32_e32 v241, v205, v251
	v_and_b32_e32 v251, 0xffff0000, v18
	v_fmac_f32_e32 v241, v233, v251
	v_lshlrev_b32_e32 v251, 16, v11
	v_mul_f32_e32 v242, v198, v251
	v_lshlrev_b32_e32 v251, 16, v15
	v_fmac_f32_e32 v242, v206, v251
	v_lshlrev_b32_e32 v251, 16, v19
	v_fmac_f32_e32 v242, v234, v251
	v_and_b32_e32 v251, 0xffff0000, v11
	v_mul_f32_e32 v243, v199, v251
	v_and_b32_e32 v251, 0xffff0000, v15
	v_fmac_f32_e32 v243, v207, v251
	v_and_b32_e32 v251, 0xffff0000, v19
	v_fmac_f32_e32 v243, v235, v251
	v_mul_f32_e32 v251, v248, v236
	v_exp_f32_e32 v251, v251
	s_nop 0
	v_add_f32_e32 v251, 1.0, v251
	v_rcp_f32_e32 v251, v251
	s_nop 0
	v_fma_f32 v251, v251, v249, v250
	v_cndmask_b32_e64 v236, v251, v236, s[36:37]
	v_mul_f32_e32 v251, v248, v237
	v_exp_f32_e32 v251, v251
	s_nop 0
	v_add_f32_e32 v251, 1.0, v251
	v_rcp_f32_e32 v251, v251
	s_nop 0
	v_fma_f32 v251, v251, v249, v250
	v_cndmask_b32_e64 v237, v251, v237, s[36:37]
	v_mul_f32_e32 v251, v248, v238
	v_exp_f32_e32 v251, v251
	s_nop 0
	v_add_f32_e32 v251, 1.0, v251
	v_rcp_f32_e32 v251, v251
	s_nop 0
	v_fma_f32 v251, v251, v249, v250
	v_cndmask_b32_e64 v238, v251, v238, s[36:37]
	v_mul_f32_e32 v251, v248, v239
	v_exp_f32_e32 v251, v251
	s_nop 0
	v_add_f32_e32 v251, 1.0, v251
	v_rcp_f32_e32 v251, v251
	s_nop 0
	v_fma_f32 v251, v251, v249, v250
	v_cndmask_b32_e64 v239, v251, v239, s[36:37]
	v_mul_f32_e32 v251, v248, v240
	v_exp_f32_e32 v251, v251
	s_nop 0
	v_add_f32_e32 v251, 1.0, v251
	v_rcp_f32_e32 v251, v251
	s_nop 0
	v_fma_f32 v251, v251, v249, v250
	v_cndmask_b32_e64 v240, v251, v240, s[36:37]
	v_mul_f32_e32 v251, v248, v241
	v_exp_f32_e32 v251, v251
	s_nop 0
	v_add_f32_e32 v251, 1.0, v251
	v_rcp_f32_e32 v251, v251
	s_nop 0
	v_fma_f32 v251, v251, v249, v250
	v_cndmask_b32_e64 v241, v251, v241, s[36:37]
	v_mul_f32_e32 v251, v248, v242
	v_exp_f32_e32 v251, v251
	s_nop 0
	v_add_f32_e32 v251, 1.0, v251
	v_rcp_f32_e32 v251, v251
	s_nop 0
	v_fma_f32 v251, v251, v249, v250
	v_cndmask_b32_e64 v242, v251, v242, s[36:37]
	v_mul_f32_e32 v251, v248, v243
	v_exp_f32_e32 v251, v251
	s_nop 0
	v_add_f32_e32 v251, 1.0, v251
	v_rcp_f32_e32 v251, v251
	s_nop 0
	v_fma_f32 v251, v251, v249, v250
	v_cndmask_b32_e64 v243, v251, v243, s[36:37]
	v_cvt_pk_bf16_f32 v236, v236, v237
	v_cvt_pk_bf16_f32 v237, v238, v239
	v_cvt_pk_bf16_f32 v238, v240, v241
	v_cvt_pk_bf16_f32 v239, v242, v243
	global_store_dwordx4 v246, v[236:239], s[2:3] offset:768
	s_nop 1
	v_lshlrev_b32_e32 v251, 16, v12
	v_mul_f32_e32 v236, v192, v251
	v_lshlrev_b32_e32 v251, 16, v16
	v_fmac_f32_e32 v236, v200, v251
	v_lshlrev_b32_e32 v251, 16, v20
	v_fmac_f32_e32 v236, v208, v251
	v_and_b32_e32 v251, 0xffff0000, v12
	v_mul_f32_e32 v237, v193, v251
	v_and_b32_e32 v251, 0xffff0000, v16
	v_fmac_f32_e32 v237, v201, v251
	v_and_b32_e32 v251, 0xffff0000, v20
	v_fmac_f32_e32 v237, v209, v251
	v_lshlrev_b32_e32 v251, 16, v13
	v_mul_f32_e32 v238, v194, v251
	v_lshlrev_b32_e32 v251, 16, v17
	v_fmac_f32_e32 v238, v202, v251
	v_lshlrev_b32_e32 v251, 16, v21
	v_fmac_f32_e32 v238, v210, v251
	v_and_b32_e32 v251, 0xffff0000, v13
	v_mul_f32_e32 v239, v195, v251
	v_and_b32_e32 v251, 0xffff0000, v17
	v_fmac_f32_e32 v239, v203, v251
	v_and_b32_e32 v251, 0xffff0000, v21
	v_fmac_f32_e32 v239, v211, v251
	v_lshlrev_b32_e32 v251, 16, v14
	v_mul_f32_e32 v240, v196, v251
	v_lshlrev_b32_e32 v251, 16, v18
	v_fmac_f32_e32 v240, v204, v251
	v_lshlrev_b32_e32 v251, 16, v22
	v_fmac_f32_e32 v240, v232, v251
	v_and_b32_e32 v251, 0xffff0000, v14
	v_mul_f32_e32 v241, v197, v251
	v_and_b32_e32 v251, 0xffff0000, v18
	v_fmac_f32_e32 v241, v205, v251
	v_and_b32_e32 v251, 0xffff0000, v22
	v_fmac_f32_e32 v241, v233, v251
	v_lshlrev_b32_e32 v251, 16, v15
	v_mul_f32_e32 v242, v198, v251
	v_lshlrev_b32_e32 v251, 16, v19
	v_fmac_f32_e32 v242, v206, v251
	v_lshlrev_b32_e32 v251, 16, v23
	v_fmac_f32_e32 v242, v234, v251
	v_and_b32_e32 v251, 0xffff0000, v15
	v_mul_f32_e32 v243, v199, v251
	v_and_b32_e32 v251, 0xffff0000, v19
	v_fmac_f32_e32 v243, v207, v251
	v_and_b32_e32 v251, 0xffff0000, v23
	v_fmac_f32_e32 v243, v235, v251
	v_mul_f32_e32 v251, v248, v236
	v_exp_f32_e32 v251, v251
	s_nop 0
	v_add_f32_e32 v251, 1.0, v251
	v_rcp_f32_e32 v251, v251
	s_nop 0
	v_fma_f32 v251, v251, v249, v250
	v_cndmask_b32_e64 v236, v251, v236, s[36:37]
	v_mul_f32_e32 v251, v248, v237
	v_exp_f32_e32 v251, v251
	s_nop 0
	v_add_f32_e32 v251, 1.0, v251
	v_rcp_f32_e32 v251, v251
	s_nop 0
	v_fma_f32 v251, v251, v249, v250
	v_cndmask_b32_e64 v237, v251, v237, s[36:37]
	v_mul_f32_e32 v251, v248, v238
	v_exp_f32_e32 v251, v251
	s_nop 0
	v_add_f32_e32 v251, 1.0, v251
	v_rcp_f32_e32 v251, v251
	s_nop 0
	v_fma_f32 v251, v251, v249, v250
	v_cndmask_b32_e64 v238, v251, v238, s[36:37]
	v_mul_f32_e32 v251, v248, v239
	v_exp_f32_e32 v251, v251
	s_nop 0
	v_add_f32_e32 v251, 1.0, v251
	v_rcp_f32_e32 v251, v251
	s_nop 0
	v_fma_f32 v251, v251, v249, v250
	v_cndmask_b32_e64 v239, v251, v239, s[36:37]
	v_mul_f32_e32 v251, v248, v240
	v_exp_f32_e32 v251, v251
	s_nop 0
	v_add_f32_e32 v251, 1.0, v251
	v_rcp_f32_e32 v251, v251
	s_nop 0
	v_fma_f32 v251, v251, v249, v250
	v_cndmask_b32_e64 v240, v251, v240, s[36:37]
	v_mul_f32_e32 v251, v248, v241
	v_exp_f32_e32 v251, v251
	s_nop 0
	v_add_f32_e32 v251, 1.0, v251
	v_rcp_f32_e32 v251, v251
	s_nop 0
	v_fma_f32 v251, v251, v249, v250
	v_cndmask_b32_e64 v241, v251, v241, s[36:37]
	v_mul_f32_e32 v251, v248, v242
	v_exp_f32_e32 v251, v251
	s_nop 0
	v_add_f32_e32 v251, 1.0, v251
	v_rcp_f32_e32 v251, v251
	s_nop 0
	v_fma_f32 v251, v251, v249, v250
	v_cndmask_b32_e64 v242, v251, v242, s[36:37]
	v_mul_f32_e32 v251, v248, v243
	v_exp_f32_e32 v251, v251
	s_nop 0
	v_add_f32_e32 v251, 1.0, v251
	v_rcp_f32_e32 v251, v251
	s_nop 0
	v_fma_f32 v251, v251, v249, v250
	v_cndmask_b32_e64 v243, v251, v243, s[36:37]
	v_cvt_pk_bf16_f32 v236, v236, v237
	v_cvt_pk_bf16_f32 v237, v238, v239
	v_cvt_pk_bf16_f32 v238, v240, v241
	v_cvt_pk_bf16_f32 v239, v242, v243
	global_store_dwordx4 v246, v[236:239], s[2:3] offset:1152
	s_nop 1
	s_or_b64 exec, exec, s[18:19]
